# gdn_chain rewritten by hand: f32 MFMA 16x16x4 recurrence, operands loaded from global directly in MFMA layout, 2 barriers per chunk step
# speedup vs baseline: 1.1067x; 1.1067x over previous
; DI int tid_() { int t = __builtin_amdgcn_workitem_id_x(); asm volatile("" : "+v"(t)); return t; }
; DI float4 gldf4(const void* p) { float4 r; asm volatile("global_load_dwordx4 %0, %1, off" : "=v"(r) : "v"(p) : "memory"); return r; }
; DI void gdn_chain(const Params& p, int item, char* smem) {
;   const int b = item >> 4, hh = (item >> 2) & 3, sl = item & 3, tid = tid_(), c = tid >> 2, e4 = (tid & 3) * 4;
;   float* sW = (float*)smem; float* sKD = sW + 64 * 65; float* sS = sKD + 64 * 65; float* sV = sS + 1024; float* sU = sV + 1024;
;   float* U = (float*)(p.ws + OFF_GU_); const float* W = (const float*)(p.ws + OFF_GW); const float* KD = (const float*)(p.ws + OFF_GKD);
;   float* Sg = (float*)(p.ws + OFF_GS); const float* glast = (const float*)(p.ws + OFF_GLAST);
;   const int ch0 = (b * 4 + hh) * 128;
;   __syncthreads();
;   *(float4*)(sS + tid * 4) = (float4){0.f, 0.f, 0.f, 0.f};
;   float4 rw[4], rk[4], ru;
;   { const float4* wp = (const float4*)(W + (size_t)ch0 * 4096); const float4* kp = (const float4*)(KD + (size_t)ch0 * 4096);
; #pragma unroll
;     for (int i = 0; i < 4; ++i) { rw[i] = gldf4(wp + tid + 256 * i); rk[i] = gldf4(kp + tid + 256 * i); }
;     ru = gldf4(U + (size_t)ch0 * 4096 + c * 64 + sl * 16 + e4); }
.LBB0_557:
	s_andn2_b64 vcc, exec, s[0:1]
	s_cbranch_vccnz .LBB0_566
	s_setprio 3
	s_lshl_b32 s0, s11, 5
	s_and_b32 s0, s0, 0xffffff80
	s_lshl_b32 s2, s11, 6
	s_and_b32 s2, s2, 0xc0
	s_add_i32 s0, s0, -2
	s_ashr_i32 s1, s0, 31
	s_lshl_b64 s[4:5], s[0:1], 14
	v_readlane_b32 s20, v244, 29
	v_readlane_b32 s21, v244, 30
	s_add_u32 s20, s20, s4
	s_addc_u32 s21, s21, s5
	v_readlane_b32 s22, v244, 31
	v_readlane_b32 s23, v244, 32
	s_add_u32 s22, s22, s4
	s_addc_u32 s23, s23, s5
	v_readlane_b32 s8, v244, 13
	v_readlane_b32 s9, v244, 14
	s_add_u32 s8, s8, s4
	s_addc_u32 s9, s9, s5
	v_readlane_b32 s12, v244, 15
	v_readlane_b32 s13, v244, 16
	s_add_u32 s12, s12, s4
	s_addc_u32 s13, s13, s5
	s_lshl_b64 s[0:1], s[0:1], 2
	v_readlane_b32 s4, v244, 33
	v_readlane_b32 s5, v244, 34
	s_add_u32 s4, s4, s0
	s_addc_u32 s5, s5, s1
	v_and_b32_e32 v146, 15, v170
	v_bfe_u32 v147, v170, 4, 2
	v_lshrrev_b32_e32 v148, 6, v170
	v_lshl_add_u32 v136, v148, 4, v146
	v_lshlrev_b32_e32 v136, 8, v136
	v_lshl_add_u32 v136, v147, 6, v136
	v_add_u32_e32 v136, 0x8000, v136
	v_lshlrev_b32_e32 v137, 12, v147
	v_lshl_add_u32 v137, v148, 6, v137
	v_lshl_add_u32 v137, v146, 2, v137
	v_add_u32_e32 v137, 0x8000, v137
	v_lshlrev_b32_e32 v138, 12, v148
	v_lshl_add_u32 v138, v147, 10, v138
	v_lshl_add_u32 v138, v146, 2, v138
	v_add_u32_e32 v138, s2, v138
	v_add_u32_e32 v139, 0x8000, v138
	v_mul_u32_u24_e32 v140, 0x110, v146
	v_lshl_add_u32 v145, v147, 6, v140
	v_lshl_add_u32 v140, v148, 6, v140
	v_lshl_add_u32 v140, v147, 4, v140
	global_load_dwordx4 v[0:3], v136, s[20:21]
	global_load_dwordx4 v[4:7], v136, s[20:21] offset:16
	global_load_dwordx4 v[8:11], v136, s[20:21] offset:32
	global_load_dwordx4 v[12:15], v136, s[20:21] offset:48
	global_load_dword v32, v139, s[8:9]
	global_load_dword v33, v139, s[8:9] offset:256
	global_load_dword v34, v139, s[8:9] offset:512
	global_load_dword v35, v139, s[8:9] offset:768
	global_load_dword v16, v137, s[22:23]
	global_load_dword v17, v137, s[22:23] offset:256
	global_load_dword v18, v137, s[22:23] offset:512
	global_load_dword v19, v137, s[22:23] offset:768
	global_load_dword v20, v137, s[22:23] offset:1024
	global_load_dword v21, v137, s[22:23] offset:1280
	global_load_dword v22, v137, s[22:23] offset:1536
	global_load_dword v23, v137, s[22:23] offset:1792
	global_load_dword v24, v137, s[22:23] offset:2048
	global_load_dword v25, v137, s[22:23] offset:2304
	global_load_dword v26, v137, s[22:23] offset:2560
	global_load_dword v27, v137, s[22:23] offset:2816
	global_load_dword v28, v137, s[22:23] offset:3072
	global_load_dword v29, v137, s[22:23] offset:3328
	global_load_dword v30, v137, s[22:23] offset:3584
	global_load_dword v31, v137, s[22:23] offset:3840
	global_load_dword v36, v143, s[4:5] offset:8
	s_add_u32 s20, s20, 0x4000
	s_addc_u32 s21, s21, 0
	s_add_u32 s22, s22, 0x4000
	s_addc_u32 s23, s23, 0
	s_add_u32 s8, s8, 0x4000
	s_addc_u32 s9, s9, 0
	s_add_u32 s12, s12, 0x4000
	s_addc_u32 s13, s13, 0
	s_add_u32 s4, s4, 4
	s_addc_u32 s5, s5, 0
	global_load_dwordx4 v[40:43], v136, s[20:21]
	global_load_dwordx4 v[44:47], v136, s[20:21] offset:16
	global_load_dwordx4 v[48:51], v136, s[20:21] offset:32
	global_load_dwordx4 v[52:55], v136, s[20:21] offset:48
	global_load_dword v72, v139, s[8:9]
	global_load_dword v73, v139, s[8:9] offset:256
	global_load_dword v74, v139, s[8:9] offset:512
	global_load_dword v75, v139, s[8:9] offset:768
	global_load_dword v56, v137, s[22:23]
	global_load_dword v57, v137, s[22:23] offset:256
	global_load_dword v58, v137, s[22:23] offset:512
	global_load_dword v59, v137, s[22:23] offset:768
	global_load_dword v60, v137, s[22:23] offset:1024
	global_load_dword v61, v137, s[22:23] offset:1280
	global_load_dword v62, v137, s[22:23] offset:1536
	global_load_dword v63, v137, s[22:23] offset:1792
	global_load_dword v64, v137, s[22:23] offset:2048
	global_load_dword v65, v137, s[22:23] offset:2304
	global_load_dword v66, v137, s[22:23] offset:2560
	global_load_dword v67, v137, s[22:23] offset:2816
	global_load_dword v68, v137, s[22:23] offset:3072
	global_load_dword v69, v137, s[22:23] offset:3328
	global_load_dword v70, v137, s[22:23] offset:3584
	global_load_dword v71, v137, s[22:23] offset:3840
	global_load_dword v76, v143, s[4:5] offset:8
	s_add_u32 s20, s20, 0x4000
	s_addc_u32 s21, s21, 0
	s_add_u32 s22, s22, 0x4000
	s_addc_u32 s23, s23, 0
	s_add_u32 s8, s8, 0x4000
	s_addc_u32 s9, s9, 0
	s_add_u32 s12, s12, 0x4000
	s_addc_u32 s13, s13, 0
	s_add_u32 s4, s4, 4
	s_addc_u32 s5, s5, 0
	v_mov_b32_e32 v80, 0
	v_mov_b32_e32 v81, 0
	v_mov_b32_e32 v82, 0
	v_mov_b32_e32 v83, 0
	v_mov_b32_e32 v84, 0
	v_mov_b32_e32 v85, 0
	v_mov_b32_e32 v86, 0
	v_mov_b32_e32 v87, 0
	v_mov_b32_e32 v88, 0
	v_mov_b32_e32 v89, 0
	v_mov_b32_e32 v90, 0
	v_mov_b32_e32 v91, 0
	v_mov_b32_e32 v92, 0
	v_mov_b32_e32 v93, 0
	v_mov_b32_e32 v94, 0
	v_mov_b32_e32 v95, 0
	v_mov_b32_e32 v112, 0
	v_mov_b32_e32 v113, 0
	v_mov_b32_e32 v114, 0
	v_mov_b32_e32 v115, 0
	s_mov_b32 s2, 0
	s_waitcnt vmcnt(0) lgkmcnt(0)
	s_barrier
; DI float4 gldf4(const void* p) { float4 r; asm volatile("global_load_dwordx4 %0, %1, off" : "=v"(r) : "v"(p) : "memory"); return r; }
; DI void vm_wait0() { asm volatile("s_waitcnt vmcnt(0)" ::: "memory"); }
; DI void gdn_chain(const Params& p, int item, char* smem) {
;     ...
;   for (int n = 0; n < 128; ++n) {
;     const int ch = ch0 + n;
;     vm_wait0();
;     __syncthreads();
; #pragma unroll
;     for (int i = 0; i < 4; ++i) { const int idx = (tid + 256 * i) * 4, rr = idx >> 6, cc = idx & 63;
;       float* dw = sW + rr * 65 + cc; dw[0] = rw[i].x; dw[1] = rw[i].y; dw[2] = rw[i].z; dw[3] = rw[i].w;
;       float* dk = sKD + rr * 65 + cc; dk[0] = rk[i].x; dk[1] = rk[i].y; dk[2] = rk[i].z; dk[3] = rk[i].w; }
;     *(float4*)(sU + c * 16 + e4) = ru;
;     const float gl = glast[ch];
;     __syncthreads();
;     if (n + 1 < 128) { const float4* wp = (const float4*)(W + (size_t)(ch + 1) * 4096); const float4* kp = (const float4*)(KD + (size_t)(ch + 1) * 4096);
; #pragma unroll
;       for (int i = 0; i < 4; ++i) { rw[i] = gldf4(wp + tid + 256 * i); rk[i] = gldf4(kp + tid + 256 * i); }
;       ru = gldf4(U + (size_t)(ch + 1) * 4096 + c * 64 + sl * 16 + e4); }
;     float4 acc = *(const float4*)(sU + c * 16 + e4);
; #pragma unroll 8
;     for (int d = 0; d < 64; ++d) { const float wv = sW[c * 65 + d]; const float4 sv = *(const float4*)(sS + d * 16 + e4);
;       acc.x -= wv * sv.x; acc.y -= wv * sv.y; acc.z -= wv * sv.z; acc.w -= wv * sv.w; }
;     *(float4*)(sV + c * 16 + e4) = acc;
;     *(float4*)(U + (size_t)ch * 4096 + c * 64 + sl * 16 + e4) = acc;
;     float4 sold = *(const float4*)(sS + c * 16 + e4);
;     *(float4*)(Sg + (size_t)ch * 4096 + c * 64 + sl * 16 + e4) = sold;
;     __syncthreads();
;     sold.x *= gl; sold.y *= gl; sold.z *= gl; sold.w *= gl;
; #pragma unroll 8
;     for (int cc = 0; cc < 64; ++cc) { const float kv = sKD[cc * 65 + c]; const float4 vv = *(const float4*)(sV + cc * 16 + e4);
;       sold.x += kv * vv.x; sold.y += kv * vv.y; sold.z += kv * vv.z; sold.w += kv * vv.w; }
;     *(float4*)(sS + c * 16 + e4) = sold;
;   }
.Lchain_loop:
	s_waitcnt vmcnt(62)
	s_waitcnt lgkmcnt(3)
	v_mfma_f32_16x16x4_f32 v[116:119], v0, v80, 0
	v_mfma_f32_16x16x4_f32 v[120:123], v1, v81, 0
	v_mfma_f32_16x16x4_f32 v[116:119], v2, v82, v[116:119]
	v_mfma_f32_16x16x4_f32 v[120:123], v3, v83, v[120:123]
	s_waitcnt lgkmcnt(2)
	v_mfma_f32_16x16x4_f32 v[116:119], v4, v84, v[116:119]
	v_mfma_f32_16x16x4_f32 v[120:123], v5, v85, v[120:123]
	v_mfma_f32_16x16x4_f32 v[116:119], v6, v86, v[116:119]
	v_mfma_f32_16x16x4_f32 v[120:123], v7, v87, v[120:123]
	s_waitcnt lgkmcnt(1)
	v_mfma_f32_16x16x4_f32 v[116:119], v8, v88, v[116:119]
	v_mfma_f32_16x16x4_f32 v[120:123], v9, v89, v[120:123]
	v_mfma_f32_16x16x4_f32 v[116:119], v10, v90, v[116:119]
	v_mfma_f32_16x16x4_f32 v[120:123], v11, v91, v[120:123]
	s_waitcnt lgkmcnt(0)
	v_mfma_f32_16x16x4_f32 v[116:119], v12, v92, v[116:119]
	v_mfma_f32_16x16x4_f32 v[120:123], v13, v93, v[120:123]
	v_mfma_f32_16x16x4_f32 v[116:119], v14, v94, v[116:119]
	v_mfma_f32_16x16x4_f32 v[120:123], v15, v95, v[120:123]
	global_load_dwordx4 v[0:3], v136, s[20:21]
	global_load_dwordx4 v[4:7], v136, s[20:21] offset:16
	global_load_dwordx4 v[8:11], v136, s[20:21] offset:32
	global_load_dwordx4 v[12:15], v136, s[20:21] offset:48
	s_waitcnt vmcnt(54)
	s_nop 4
	v_add_f32_e32 v116, v116, v120
	v_add_f32_e32 v117, v117, v121
	v_add_f32_e32 v118, v118, v122
	v_add_f32_e32 v119, v119, v123
	v_sub_f32_e32 v124, v32, v116
	v_sub_f32_e32 v125, v33, v117
	v_sub_f32_e32 v126, v34, v118
	v_sub_f32_e32 v127, v35, v119
	global_store_dword v138, v124, s[8:9]
	global_store_dword v138, v125, s[8:9] offset:256
	global_store_dword v138, v126, s[8:9] offset:512
	global_store_dword v138, v127, s[8:9] offset:768
	ds_write_b128 v140, v[124:127] offset:4352
	global_store_dword v138, v112, s[12:13]
	global_store_dword v138, v113, s[12:13] offset:256
	global_store_dword v138, v114, s[12:13] offset:512
	global_store_dword v138, v115, s[12:13] offset:768
	global_load_dword v32, v139, s[8:9]
	global_load_dword v33, v139, s[8:9] offset:256
	global_load_dword v34, v139, s[8:9] offset:512
	global_load_dword v35, v139, s[8:9] offset:768
	s_waitcnt lgkmcnt(0)
	s_barrier
	ds_read_b128 v[96:99], v145 offset:4352
	ds_read_b128 v[100:103], v145 offset:4368
	ds_read_b128 v[104:107], v145 offset:4384
	ds_read_b128 v[108:111], v145 offset:4400
	s_waitcnt vmcnt(49)
	v_mul_f32_e32 v128, v36, v112
	v_mul_f32_e32 v129, v36, v113
	v_mul_f32_e32 v130, v36, v114
	v_mul_f32_e32 v131, v36, v115
	s_waitcnt lgkmcnt(3)
	s_nop 0
	v_mfma_f32_16x16x4_f32 v[128:131], v16, v96, v[128:131]
	v_mfma_f32_16x16x4_f32 v[132:135], v17, v97, 0
	v_mfma_f32_16x16x4_f32 v[128:131], v18, v98, v[128:131]
	v_mfma_f32_16x16x4_f32 v[132:135], v19, v99, v[132:135]
	s_waitcnt lgkmcnt(2)
	v_mfma_f32_16x16x4_f32 v[128:131], v20, v100, v[128:131]
	v_mfma_f32_16x16x4_f32 v[132:135], v21, v101, v[132:135]
	v_mfma_f32_16x16x4_f32 v[128:131], v22, v102, v[128:131]
	v_mfma_f32_16x16x4_f32 v[132:135], v23, v103, v[132:135]
	s_waitcnt lgkmcnt(1)
	v_mfma_f32_16x16x4_f32 v[128:131], v24, v104, v[128:131]
	v_mfma_f32_16x16x4_f32 v[132:135], v25, v105, v[132:135]
	v_mfma_f32_16x16x4_f32 v[128:131], v26, v106, v[128:131]
	v_mfma_f32_16x16x4_f32 v[132:135], v27, v107, v[132:135]
	s_waitcnt lgkmcnt(0)
	v_mfma_f32_16x16x4_f32 v[128:131], v28, v108, v[128:131]
	v_mfma_f32_16x16x4_f32 v[132:135], v29, v109, v[132:135]
	v_mfma_f32_16x16x4_f32 v[128:131], v30, v110, v[128:131]
	v_mfma_f32_16x16x4_f32 v[132:135], v31, v111, v[132:135]
	global_load_dword v16, v137, s[22:23]
	global_load_dword v17, v137, s[22:23] offset:256
	global_load_dword v18, v137, s[22:23] offset:512
	global_load_dword v19, v137, s[22:23] offset:768
	global_load_dword v20, v137, s[22:23] offset:1024
	global_load_dword v21, v137, s[22:23] offset:1280
	global_load_dword v22, v137, s[22:23] offset:1536
	global_load_dword v23, v137, s[22:23] offset:1792
	global_load_dword v24, v137, s[22:23] offset:2048
	global_load_dword v25, v137, s[22:23] offset:2304
	global_load_dword v26, v137, s[22:23] offset:2560
	global_load_dword v27, v137, s[22:23] offset:2816
	global_load_dword v28, v137, s[22:23] offset:3072
	global_load_dword v29, v137, s[22:23] offset:3328
	global_load_dword v30, v137, s[22:23] offset:3584
	global_load_dword v31, v137, s[22:23] offset:3840
	global_load_dword v36, v143, s[4:5] offset:8
	v_add_f32_e32 v112, v128, v132
	v_add_f32_e32 v113, v129, v133
	v_add_f32_e32 v114, v130, v134
	v_add_f32_e32 v115, v131, v135
	ds_write_b128 v140, v[112:115]
	s_waitcnt lgkmcnt(0)
	s_barrier
; DI float4 gldf4(const void* p) { float4 r; asm volatile("global_load_dwordx4 %0, %1, off" : "=v"(r) : "v"(p) : "memory"); return r; }
; DI void vm_wait0() { asm volatile("s_waitcnt vmcnt(0)" ::: "memory"); }
; DI void gdn_chain(const Params& p, int item, char* smem) {
;     ...
;   for (int n = 0; n < 128; ++n) {
;     const int ch = ch0 + n;
;     vm_wait0();
;     __syncthreads();
; #pragma unroll
;     for (int i = 0; i < 4; ++i) { const int idx = (tid + 256 * i) * 4, rr = idx >> 6, cc = idx & 63;
;       float* dw = sW + rr * 65 + cc; dw[0] = rw[i].x; dw[1] = rw[i].y; dw[2] = rw[i].z; dw[3] = rw[i].w;
;       float* dk = sKD + rr * 65 + cc; dk[0] = rk[i].x; dk[1] = rk[i].y; dk[2] = rk[i].z; dk[3] = rk[i].w; }
;     *(float4*)(sU + c * 16 + e4) = ru;
;     const float gl = glast[ch];
;     __syncthreads();
;     if (n + 1 < 128) { const float4* wp = (const float4*)(W + (size_t)(ch + 1) * 4096); const float4* kp = (const float4*)(KD + (size_t)(ch + 1) * 4096);
; #pragma unroll
;       for (int i = 0; i < 4; ++i) { rw[i] = gldf4(wp + tid + 256 * i); rk[i] = gldf4(kp + tid + 256 * i); }
;       ru = gldf4(U + (size_t)(ch + 1) * 4096 + c * 64 + sl * 16 + e4); }
;     float4 acc = *(const float4*)(sU + c * 16 + e4);
; #pragma unroll 8
;     for (int d = 0; d < 64; ++d) { const float wv = sW[c * 65 + d]; const float4 sv = *(const float4*)(sS + d * 16 + e4);
;       acc.x -= wv * sv.x; acc.y -= wv * sv.y; acc.z -= wv * sv.z; acc.w -= wv * sv.w; }
;     *(float4*)(sV + c * 16 + e4) = acc;
;     *(float4*)(U + (size_t)ch * 4096 + c * 64 + sl * 16 + e4) = acc;
;     float4 sold = *(const float4*)(sS + c * 16 + e4);
;     *(float4*)(Sg + (size_t)ch * 4096 + c * 64 + sl * 16 + e4) = sold;
;     __syncthreads();
;     sold.x *= gl; sold.y *= gl; sold.z *= gl; sold.w *= gl;
; #pragma unroll 8
;     for (int cc = 0; cc < 64; ++cc) { const float kv = sKD[cc * 65 + c]; const float4 vv = *(const float4*)(sV + cc * 16 + e4);
;       sold.x += kv * vv.x; sold.y += kv * vv.y; sold.z += kv * vv.z; sold.w += kv * vv.w; }
;     *(float4*)(sS + c * 16 + e4) = sold;
;   }
	ds_read_b128 v[80:83], v145
	ds_read_b128 v[84:87], v145 offset:16
	ds_read_b128 v[88:91], v145 offset:32
	ds_read_b128 v[92:95], v145 offset:48
	s_add_u32 s20, s20, 0x4000
	s_addc_u32 s21, s21, 0
	s_add_u32 s22, s22, 0x4000
	s_addc_u32 s23, s23, 0
	s_add_u32 s8, s8, 0x4000
	s_addc_u32 s9, s9, 0
	s_add_u32 s12, s12, 0x4000
	s_addc_u32 s13, s13, 0
	s_add_u32 s4, s4, 4
	s_addc_u32 s5, s5, 0
	s_waitcnt vmcnt(62)
	s_waitcnt lgkmcnt(3)
	v_mfma_f32_16x16x4_f32 v[116:119], v40, v80, 0
	v_mfma_f32_16x16x4_f32 v[120:123], v41, v81, 0
	v_mfma_f32_16x16x4_f32 v[116:119], v42, v82, v[116:119]
	v_mfma_f32_16x16x4_f32 v[120:123], v43, v83, v[120:123]
	s_waitcnt lgkmcnt(2)
	v_mfma_f32_16x16x4_f32 v[116:119], v44, v84, v[116:119]
	v_mfma_f32_16x16x4_f32 v[120:123], v45, v85, v[120:123]
	v_mfma_f32_16x16x4_f32 v[116:119], v46, v86, v[116:119]
	v_mfma_f32_16x16x4_f32 v[120:123], v47, v87, v[120:123]
	s_waitcnt lgkmcnt(1)
	v_mfma_f32_16x16x4_f32 v[116:119], v48, v88, v[116:119]
	v_mfma_f32_16x16x4_f32 v[120:123], v49, v89, v[120:123]
	v_mfma_f32_16x16x4_f32 v[116:119], v50, v90, v[116:119]
	v_mfma_f32_16x16x4_f32 v[120:123], v51, v91, v[120:123]
	s_waitcnt lgkmcnt(0)
	v_mfma_f32_16x16x4_f32 v[116:119], v52, v92, v[116:119]
	v_mfma_f32_16x16x4_f32 v[120:123], v53, v93, v[120:123]
	v_mfma_f32_16x16x4_f32 v[116:119], v54, v94, v[116:119]
	v_mfma_f32_16x16x4_f32 v[120:123], v55, v95, v[120:123]
	global_load_dwordx4 v[40:43], v136, s[20:21]
	global_load_dwordx4 v[44:47], v136, s[20:21] offset:16
	global_load_dwordx4 v[48:51], v136, s[20:21] offset:32
	global_load_dwordx4 v[52:55], v136, s[20:21] offset:48
	s_waitcnt vmcnt(54)
	s_nop 4
	v_add_f32_e32 v116, v116, v120
	v_add_f32_e32 v117, v117, v121
	v_add_f32_e32 v118, v118, v122
	v_add_f32_e32 v119, v119, v123
	v_sub_f32_e32 v124, v72, v116
	v_sub_f32_e32 v125, v73, v117
	v_sub_f32_e32 v126, v74, v118
	v_sub_f32_e32 v127, v75, v119
	global_store_dword v138, v124, s[8:9]
	global_store_dword v138, v125, s[8:9] offset:256
	global_store_dword v138, v126, s[8:9] offset:512
	global_store_dword v138, v127, s[8:9] offset:768
	ds_write_b128 v140, v[124:127] offset:4352
	global_store_dword v138, v112, s[12:13]
	global_store_dword v138, v113, s[12:13] offset:256
	global_store_dword v138, v114, s[12:13] offset:512
	global_store_dword v138, v115, s[12:13] offset:768
	global_load_dword v72, v139, s[8:9]
	global_load_dword v73, v139, s[8:9] offset:256
	global_load_dword v74, v139, s[8:9] offset:512
	global_load_dword v75, v139, s[8:9] offset:768
	s_waitcnt lgkmcnt(0)
	s_barrier
	ds_read_b128 v[96:99], v145 offset:4352
	ds_read_b128 v[100:103], v145 offset:4368
	ds_read_b128 v[104:107], v145 offset:4384
	ds_read_b128 v[108:111], v145 offset:4400
	s_waitcnt vmcnt(49)
	v_mul_f32_e32 v128, v76, v112
	v_mul_f32_e32 v129, v76, v113
	v_mul_f32_e32 v130, v76, v114
	v_mul_f32_e32 v131, v76, v115
	s_waitcnt lgkmcnt(3)
	s_nop 0
	v_mfma_f32_16x16x4_f32 v[128:131], v56, v96, v[128:131]
	v_mfma_f32_16x16x4_f32 v[132:135], v57, v97, 0
	v_mfma_f32_16x16x4_f32 v[128:131], v58, v98, v[128:131]
	v_mfma_f32_16x16x4_f32 v[132:135], v59, v99, v[132:135]
	s_waitcnt lgkmcnt(2)
	v_mfma_f32_16x16x4_f32 v[128:131], v60, v100, v[128:131]
	v_mfma_f32_16x16x4_f32 v[132:135], v61, v101, v[132:135]
	v_mfma_f32_16x16x4_f32 v[128:131], v62, v102, v[128:131]
	v_mfma_f32_16x16x4_f32 v[132:135], v63, v103, v[132:135]
	s_waitcnt lgkmcnt(1)
	v_mfma_f32_16x16x4_f32 v[128:131], v64, v104, v[128:131]
	v_mfma_f32_16x16x4_f32 v[132:135], v65, v105, v[132:135]
	v_mfma_f32_16x16x4_f32 v[128:131], v66, v106, v[128:131]
	v_mfma_f32_16x16x4_f32 v[132:135], v67, v107, v[132:135]
	s_waitcnt lgkmcnt(0)
	v_mfma_f32_16x16x4_f32 v[128:131], v68, v108, v[128:131]
	v_mfma_f32_16x16x4_f32 v[132:135], v69, v109, v[132:135]
	v_mfma_f32_16x16x4_f32 v[128:131], v70, v110, v[128:131]
	v_mfma_f32_16x16x4_f32 v[132:135], v71, v111, v[132:135]
	global_load_dword v56, v137, s[22:23]
	global_load_dword v57, v137, s[22:23] offset:256
	global_load_dword v58, v137, s[22:23] offset:512
	global_load_dword v59, v137, s[22:23] offset:768
	global_load_dword v60, v137, s[22:23] offset:1024
	global_load_dword v61, v137, s[22:23] offset:1280
	global_load_dword v62, v137, s[22:23] offset:1536
	global_load_dword v63, v137, s[22:23] offset:1792
	global_load_dword v64, v137, s[22:23] offset:2048
	global_load_dword v65, v137, s[22:23] offset:2304
	global_load_dword v66, v137, s[22:23] offset:2560
	global_load_dword v67, v137, s[22:23] offset:2816
	global_load_dword v68, v137, s[22:23] offset:3072
	global_load_dword v69, v137, s[22:23] offset:3328
	global_load_dword v70, v137, s[22:23] offset:3584
	global_load_dword v71, v137, s[22:23] offset:3840
	global_load_dword v76, v143, s[4:5] offset:8
	v_add_f32_e32 v112, v128, v132
	v_add_f32_e32 v113, v129, v133
	v_add_f32_e32 v114, v130, v134
	v_add_f32_e32 v115, v131, v135
	ds_write_b128 v140, v[112:115]
	s_waitcnt lgkmcnt(0)
	s_barrier
	ds_read_b128 v[80:83], v145
	ds_read_b128 v[84:87], v145 offset:16
	ds_read_b128 v[88:91], v145 offset:32
	ds_read_b128 v[92:95], v145 offset:48
	s_add_u32 s20, s20, 0x4000
	s_addc_u32 s21, s21, 0
	s_add_u32 s22, s22, 0x4000
	s_addc_u32 s23, s23, 0
	s_add_u32 s8, s8, 0x4000
	s_addc_u32 s9, s9, 0
	s_add_u32 s12, s12, 0x4000
	s_addc_u32 s13, s13, 0
	s_add_u32 s4, s4, 4
	s_addc_u32 s5, s5, 0
	s_add_i32 s2, s2, 2
	s_cmpk_eq_i32 s2, 0x80
	s_cbranch_scc0 .Lchain_loop
	s_waitcnt vmcnt(0) lgkmcnt(0)
	s_setprio 0
